# phase 0 GEMV: 26 of the 32 weight-row loads of a K block requested before the first accumulate (second round trip mostly hidden)
# speedup vs baseline: 1.0229x; 1.0031x over previous
.LBB0_8:
	s_cmpk_gt_i32 s2, 0xbf
	s_cbranch_scc1 .Lgv_end
	s_load_dwordx2 s[30:31], s[8:9], 0x28
	s_load_dwordx2 s[28:29], s[8:9], 0x30
	s_load_dwordx2 s[34:35], s[8:9], 0x40
	s_load_dwordx2 s[36:37], s[8:9], 0x48
	s_cmpk_gt_i32 s2, 0x5f
	s_cselect_b32 s14, 1, 0
	s_mul_i32 s15, s14, 0x60
	s_sub_i32 s15, s2, s15
	s_lshl_b32 s15, s15, 6
	v_lshlrev_b32_e32 v10, 2, v1
	s_waitcnt lgkmcnt(0)
	global_load_dword v16, v10, s[28:29]
	global_load_dword v17, v10, s[28:29] offset:2048
	global_load_dword v18, v10, s[30:31]
	global_load_dword v19, v10, s[30:31] offset:2048
	v_add_u32_e32 v11, 0x1000, v10
	global_load_dword v20, v11, s[30:31]
	v_add_u32_e32 v11, 0x1800, v10
	global_load_dword v21, v11, s[30:31]
	v_add_u32_e32 v11, 0x2000, v10
	global_load_dword v22, v11, s[30:31]
	v_add_u32_e32 v11, 0x2800, v10
	global_load_dword v23, v11, s[30:31]
	v_add_u32_e32 v11, 0x3000, v10
	global_load_dword v24, v11, s[30:31]
	v_add_u32_e32 v11, 0x3800, v10
	global_load_dword v25, v11, s[30:31]
	s_waitcnt vmcnt(9)
	v_mov_b32_e32 v2, v16
	v_mul_f32_e32 v4, 0xbfb8aa3b, v2
	v_rndne_f32_e32 v5, v4
	v_fma_f32 v6, v2, s3, -v4
	v_sub_f32_e32 v4, v4, v5
	v_fmac_f32_e32 v6, 0xb2a5705f, v2
	v_add_f32_e32 v4, v4, v6
	v_cvt_i32_f32_e32 v5, v5
	v_exp_f32_e32 v4, v4
	v_cmp_nlt_f32_e32 vcc, s18, v2
	v_ldexp_f32 v4, v4, v5
	s_nop 0
	v_cndmask_b32_e32 v4, 0, v4, vcc
	v_cmp_ngt_f32_e32 vcc, s19, v2
	s_nop 1
	v_cndmask_b32_e32 v4, v15, v4, vcc
	v_add_f32_e32 v4, 1.0, v4
	v_div_scale_f32 v5, s[22:23], v4, v4, v2
	v_rcp_f32_e32 v6, v5
	v_div_scale_f32 v7, vcc, v2, v4, v2
	v_fma_f32 v8, -v5, v6, 1.0
	v_fmac_f32_e32 v6, v8, v6
	v_mul_f32_e32 v8, v7, v6
	v_fma_f32 v9, -v5, v8, v7
	v_fmac_f32_e32 v8, v9, v6
	v_fma_f32 v5, -v5, v8, v7
	v_div_fmas_f32 v5, v5, v6, v8
	v_div_fixup_f32 v2, v5, v4, v2
	ds_write_b32 v10, v2
	s_waitcnt vmcnt(8)
	v_mov_b32_e32 v2, v17
	v_mul_f32_e32 v4, 0xbfb8aa3b, v2
	v_rndne_f32_e32 v5, v4
	v_fma_f32 v6, v2, s3, -v4
	v_sub_f32_e32 v4, v4, v5
	v_fmac_f32_e32 v6, 0xb2a5705f, v2
	v_add_f32_e32 v4, v4, v6
	v_cvt_i32_f32_e32 v5, v5
	v_exp_f32_e32 v4, v4
	v_cmp_nlt_f32_e32 vcc, s18, v2
	v_ldexp_f32 v4, v4, v5
	s_nop 0
	v_cndmask_b32_e32 v4, 0, v4, vcc
	v_cmp_ngt_f32_e32 vcc, s19, v2
	s_nop 1
	v_cndmask_b32_e32 v4, v15, v4, vcc
	v_add_f32_e32 v4, 1.0, v4
	v_div_scale_f32 v5, s[22:23], v4, v4, v2
	v_rcp_f32_e32 v6, v5
	v_div_scale_f32 v7, vcc, v2, v4, v2
	v_fma_f32 v8, -v5, v6, 1.0
	v_fmac_f32_e32 v6, v8, v6
	v_mul_f32_e32 v8, v7, v6
	v_fma_f32 v9, -v5, v8, v7
	v_fmac_f32_e32 v8, v9, v6
	v_fma_f32 v5, -v5, v8, v7
	v_div_fmas_f32 v5, v5, v6, v8
	v_div_fixup_f32 v2, v5, v4, v2
	ds_write_b32 v10, v2 offset:2048
	s_waitcnt vmcnt(7)
	v_mov_b32_e32 v2, v18
	v_mul_f32_e32 v4, 0xbfb8aa3b, v2
	v_rndne_f32_e32 v5, v4
	v_fma_f32 v6, v2, s3, -v4
	v_sub_f32_e32 v4, v4, v5
	v_fmac_f32_e32 v6, 0xb2a5705f, v2
	v_add_f32_e32 v4, v4, v6
	v_cvt_i32_f32_e32 v5, v5
	v_exp_f32_e32 v4, v4
	v_cmp_nlt_f32_e32 vcc, s18, v2
	v_ldexp_f32 v4, v4, v5
	s_nop 0
	v_cndmask_b32_e32 v4, 0, v4, vcc
	v_cmp_ngt_f32_e32 vcc, s19, v2
	s_nop 1
	v_cndmask_b32_e32 v4, v15, v4, vcc
	v_add_f32_e32 v4, 1.0, v4
	v_div_scale_f32 v5, s[22:23], v4, v4, v2
	v_rcp_f32_e32 v6, v5
	v_div_scale_f32 v7, vcc, v2, v4, v2
	v_fma_f32 v8, -v5, v6, 1.0
	v_fmac_f32_e32 v6, v8, v6
	v_mul_f32_e32 v8, v7, v6
	v_fma_f32 v9, -v5, v8, v7
	v_fmac_f32_e32 v8, v9, v6
	v_fma_f32 v5, -v5, v8, v7
	v_div_fmas_f32 v5, v5, v6, v8
	v_div_fixup_f32 v2, v5, v4, v2
	ds_write_b32 v10, v2 offset:4096
	s_waitcnt vmcnt(6)
	v_mov_b32_e32 v2, v19
	v_mul_f32_e32 v4, 0xbfb8aa3b, v2
	v_rndne_f32_e32 v5, v4
	v_fma_f32 v6, v2, s3, -v4
	v_sub_f32_e32 v4, v4, v5
	v_fmac_f32_e32 v6, 0xb2a5705f, v2
	v_add_f32_e32 v4, v4, v6
	v_cvt_i32_f32_e32 v5, v5
	v_exp_f32_e32 v4, v4
	v_cmp_nlt_f32_e32 vcc, s18, v2
	v_ldexp_f32 v4, v4, v5
	s_nop 0
	v_cndmask_b32_e32 v4, 0, v4, vcc
	v_cmp_ngt_f32_e32 vcc, s19, v2
	s_nop 1
	v_cndmask_b32_e32 v4, v15, v4, vcc
	v_add_f32_e32 v4, 1.0, v4
	v_div_scale_f32 v5, s[22:23], v4, v4, v2
	v_rcp_f32_e32 v6, v5
	v_div_scale_f32 v7, vcc, v2, v4, v2
	v_fma_f32 v8, -v5, v6, 1.0
	v_fmac_f32_e32 v6, v8, v6
	v_mul_f32_e32 v8, v7, v6
	v_fma_f32 v9, -v5, v8, v7
	v_fmac_f32_e32 v8, v9, v6
	v_fma_f32 v5, -v5, v8, v7
	v_div_fmas_f32 v5, v5, v6, v8
	v_div_fixup_f32 v2, v5, v4, v2
	ds_write_b32 v10, v2 offset:6144
	s_waitcnt vmcnt(5)
	v_mov_b32_e32 v2, v20
	v_mul_f32_e32 v4, 0xbfb8aa3b, v2
	v_rndne_f32_e32 v5, v4
	v_fma_f32 v6, v2, s3, -v4
	v_sub_f32_e32 v4, v4, v5
	v_fmac_f32_e32 v6, 0xb2a5705f, v2
	v_add_f32_e32 v4, v4, v6
	v_cvt_i32_f32_e32 v5, v5
	v_exp_f32_e32 v4, v4
	v_cmp_nlt_f32_e32 vcc, s18, v2
	v_ldexp_f32 v4, v4, v5
	s_nop 0
	v_cndmask_b32_e32 v4, 0, v4, vcc
	v_cmp_ngt_f32_e32 vcc, s19, v2
	s_nop 1
	v_cndmask_b32_e32 v4, v15, v4, vcc
	v_add_f32_e32 v4, 1.0, v4
	v_div_scale_f32 v5, s[22:23], v4, v4, v2
	v_rcp_f32_e32 v6, v5
	v_div_scale_f32 v7, vcc, v2, v4, v2
	v_fma_f32 v8, -v5, v6, 1.0
	v_fmac_f32_e32 v6, v8, v6
	v_mul_f32_e32 v8, v7, v6
	v_fma_f32 v9, -v5, v8, v7
	v_fmac_f32_e32 v8, v9, v6
	v_fma_f32 v5, -v5, v8, v7
	v_div_fmas_f32 v5, v5, v6, v8
	v_div_fixup_f32 v2, v5, v4, v2
	ds_write_b32 v10, v2 offset:8192
	s_waitcnt vmcnt(4)
	v_mov_b32_e32 v2, v21
	v_mul_f32_e32 v4, 0xbfb8aa3b, v2
	v_rndne_f32_e32 v5, v4
	v_fma_f32 v6, v2, s3, -v4
	v_sub_f32_e32 v4, v4, v5
	v_fmac_f32_e32 v6, 0xb2a5705f, v2
	v_add_f32_e32 v4, v4, v6
	v_cvt_i32_f32_e32 v5, v5
	v_exp_f32_e32 v4, v4
	v_cmp_nlt_f32_e32 vcc, s18, v2
	v_ldexp_f32 v4, v4, v5
	s_nop 0
	v_cndmask_b32_e32 v4, 0, v4, vcc
	v_cmp_ngt_f32_e32 vcc, s19, v2
	s_nop 1
	v_cndmask_b32_e32 v4, v15, v4, vcc
	v_add_f32_e32 v4, 1.0, v4
	v_div_scale_f32 v5, s[22:23], v4, v4, v2
	v_rcp_f32_e32 v6, v5
	v_div_scale_f32 v7, vcc, v2, v4, v2
	v_fma_f32 v8, -v5, v6, 1.0
	v_fmac_f32_e32 v6, v8, v6
	v_mul_f32_e32 v8, v7, v6
	v_fma_f32 v9, -v5, v8, v7
	v_fmac_f32_e32 v8, v9, v6
	v_fma_f32 v5, -v5, v8, v7
	v_div_fmas_f32 v5, v5, v6, v8
	v_div_fixup_f32 v2, v5, v4, v2
	ds_write_b32 v10, v2 offset:10240
	s_waitcnt vmcnt(3)
	v_mov_b32_e32 v2, v22
	v_mul_f32_e32 v4, 0xbfb8aa3b, v2
	v_rndne_f32_e32 v5, v4
	v_fma_f32 v6, v2, s3, -v4
	v_sub_f32_e32 v4, v4, v5
	v_fmac_f32_e32 v6, 0xb2a5705f, v2
	v_add_f32_e32 v4, v4, v6
	v_cvt_i32_f32_e32 v5, v5
	v_exp_f32_e32 v4, v4
	v_cmp_nlt_f32_e32 vcc, s18, v2
	v_ldexp_f32 v4, v4, v5
	s_nop 0
	v_cndmask_b32_e32 v4, 0, v4, vcc
	v_cmp_ngt_f32_e32 vcc, s19, v2
	s_nop 1
	v_cndmask_b32_e32 v4, v15, v4, vcc
	v_add_f32_e32 v4, 1.0, v4
	v_div_scale_f32 v5, s[22:23], v4, v4, v2
	v_rcp_f32_e32 v6, v5
	v_div_scale_f32 v7, vcc, v2, v4, v2
	v_fma_f32 v8, -v5, v6, 1.0
	v_fmac_f32_e32 v6, v8, v6
	v_mul_f32_e32 v8, v7, v6
	v_fma_f32 v9, -v5, v8, v7
	v_fmac_f32_e32 v8, v9, v6
	v_fma_f32 v5, -v5, v8, v7
	v_div_fmas_f32 v5, v5, v6, v8
	v_div_fixup_f32 v2, v5, v4, v2
	ds_write_b32 v10, v2 offset:12288
	s_waitcnt vmcnt(2)
	v_mov_b32_e32 v2, v23
	v_mul_f32_e32 v4, 0xbfb8aa3b, v2
	v_rndne_f32_e32 v5, v4
	v_fma_f32 v6, v2, s3, -v4
	v_sub_f32_e32 v4, v4, v5
	v_fmac_f32_e32 v6, 0xb2a5705f, v2
	v_add_f32_e32 v4, v4, v6
	v_cvt_i32_f32_e32 v5, v5
	v_exp_f32_e32 v4, v4
	v_cmp_nlt_f32_e32 vcc, s18, v2
	v_ldexp_f32 v4, v4, v5
	s_nop 0
	v_cndmask_b32_e32 v4, 0, v4, vcc
	v_cmp_ngt_f32_e32 vcc, s19, v2
	s_nop 1
	v_cndmask_b32_e32 v4, v15, v4, vcc
	v_add_f32_e32 v4, 1.0, v4
	v_div_scale_f32 v5, s[22:23], v4, v4, v2
	v_rcp_f32_e32 v6, v5
	v_div_scale_f32 v7, vcc, v2, v4, v2
	v_fma_f32 v8, -v5, v6, 1.0
	v_fmac_f32_e32 v6, v8, v6
	v_mul_f32_e32 v8, v7, v6
	v_fma_f32 v9, -v5, v8, v7
	v_fmac_f32_e32 v8, v9, v6
	v_fma_f32 v5, -v5, v8, v7
	v_div_fmas_f32 v5, v5, v6, v8
	v_div_fixup_f32 v2, v5, v4, v2
	ds_write_b32 v10, v2 offset:14336
	s_waitcnt vmcnt(1)
	v_mov_b32_e32 v2, v24
	v_mul_f32_e32 v4, 0xbfb8aa3b, v2
	v_rndne_f32_e32 v5, v4
	v_fma_f32 v6, v2, s3, -v4
	v_sub_f32_e32 v4, v4, v5
	v_fmac_f32_e32 v6, 0xb2a5705f, v2
	v_add_f32_e32 v4, v4, v6
	v_cvt_i32_f32_e32 v5, v5
	v_exp_f32_e32 v4, v4
	v_cmp_nlt_f32_e32 vcc, s18, v2
	v_ldexp_f32 v4, v4, v5
	s_nop 0
	v_cndmask_b32_e32 v4, 0, v4, vcc
	v_cmp_ngt_f32_e32 vcc, s19, v2
	s_nop 1
	v_cndmask_b32_e32 v4, v15, v4, vcc
	v_add_f32_e32 v4, 1.0, v4
	v_div_scale_f32 v5, s[22:23], v4, v4, v2
	v_rcp_f32_e32 v6, v5
	v_div_scale_f32 v7, vcc, v2, v4, v2
	v_fma_f32 v8, -v5, v6, 1.0
	v_fmac_f32_e32 v6, v8, v6
	v_mul_f32_e32 v8, v7, v6
	v_fma_f32 v9, -v5, v8, v7
	v_fmac_f32_e32 v8, v9, v6
	v_fma_f32 v5, -v5, v8, v7
	v_div_fmas_f32 v5, v5, v6, v8
	v_div_fixup_f32 v2, v5, v4, v2
	ds_write_b32 v10, v2 offset:16384
	s_waitcnt vmcnt(0)
	v_mov_b32_e32 v2, v25
	v_mul_f32_e32 v4, 0xbfb8aa3b, v2
	v_rndne_f32_e32 v5, v4
	v_fma_f32 v6, v2, s3, -v4
	v_sub_f32_e32 v4, v4, v5
	v_fmac_f32_e32 v6, 0xb2a5705f, v2
	v_add_f32_e32 v4, v4, v6
	v_cvt_i32_f32_e32 v5, v5
	v_exp_f32_e32 v4, v4
	v_cmp_nlt_f32_e32 vcc, s18, v2
	v_ldexp_f32 v4, v4, v5
	s_nop 0
	v_cndmask_b32_e32 v4, 0, v4, vcc
	v_cmp_ngt_f32_e32 vcc, s19, v2
	s_nop 1
	v_cndmask_b32_e32 v4, v15, v4, vcc
	v_add_f32_e32 v4, 1.0, v4
	v_div_scale_f32 v5, s[22:23], v4, v4, v2
	v_rcp_f32_e32 v6, v5
	v_div_scale_f32 v7, vcc, v2, v4, v2
	v_fma_f32 v8, -v5, v6, 1.0
	v_fmac_f32_e32 v6, v8, v6
	v_mul_f32_e32 v8, v7, v6
	v_fma_f32 v9, -v5, v8, v7
	v_fmac_f32_e32 v8, v9, v6
	v_fma_f32 v5, -v5, v8, v7
	v_div_fmas_f32 v5, v5, v6, v8
	v_div_fixup_f32 v2, v5, v4, v2
	ds_write_b32 v10, v2 offset:18432
	s_waitcnt lgkmcnt(0)
	s_barrier
	v_readfirstlane_b32 s16, v1
	s_lshr_b32 s16, s16, 6
	v_and_b32_e32 v11, 63, v1
	v_and_b32_e32 v12, 15, v11
	v_lshrrev_b32_e32 v13, 4, v11
	v_lshlrev_b32_e32 v14, 4, v12
	s_lshl_b32 s17, s15, 2
	v_add_u32_e32 v14, s17, v14
	v_mul_u32_u24_e32 v11, 0xc0000, v13
	v_add_u32_e32 v14, v11, v14
	s_mul_i32 s20, s14, 0x1800000
	s_mul_i32 s21, s16, 0x300000
	s_add_u32 s20, s20, s21
	s_add_u32 s20, s12, s20
	s_addc_u32 s21, s13, 0
	v_lshl_add_u32 v11, s16, 2, v13
	v_lshlrev_b32_e32 v11, 7, v11
	v_mov_b32_e32 v100, 0
	v_mov_b32_e32 v101, 0
	v_mov_b32_e32 v102, 0
	v_mov_b32_e32 v103, 0
	v_mov_b32_e32 v104, 0
	v_mov_b32_e32 v105, 0
	v_mov_b32_e32 v106, 0
	v_mov_b32_e32 v107, 0
	v_mov_b32_e32 v108, 0
	v_mov_b32_e32 v109, 0
	v_mov_b32_e32 v110, 0
	v_mov_b32_e32 v111, 0
	v_mov_b32_e32 v112, 0
	v_mov_b32_e32 v113, 0
	v_mov_b32_e32 v114, 0
	v_mov_b32_e32 v115, 0
	v_mov_b32_e32 v116, 0
	v_mov_b32_e32 v117, 0
	v_mov_b32_e32 v118, 0
	v_mov_b32_e32 v119, 0
	global_load_dwordx4 v[16:19], v14, s[20:21] nt
	s_add_u32 s20, s20, 0x6000
	s_addc_u32 s21, s21, 0
	global_load_dwordx4 v[20:23], v14, s[20:21] nt
	s_add_u32 s20, s20, 0x6000
	s_addc_u32 s21, s21, 0
	global_load_dwordx4 v[24:27], v14, s[20:21] nt
	s_add_u32 s20, s20, 0x6000
	s_addc_u32 s21, s21, 0
	global_load_dwordx4 v[28:31], v14, s[20:21] nt
	s_add_u32 s20, s20, 0x6000
	s_addc_u32 s21, s21, 0
	global_load_dwordx4 v[32:35], v14, s[20:21] nt
	s_add_u32 s20, s20, 0x6000
	s_addc_u32 s21, s21, 0
	global_load_dwordx4 v[36:39], v14, s[20:21] nt
	s_add_u32 s20, s20, 0x6000
	s_addc_u32 s21, s21, 0
	global_load_dwordx4 v[40:43], v14, s[20:21] nt
	s_add_u32 s20, s20, 0x6000
	s_addc_u32 s21, s21, 0
	global_load_dwordx4 v[44:47], v14, s[20:21] nt
	s_add_u32 s20, s20, 0x6000
	s_addc_u32 s21, s21, 0
	global_load_dwordx4 v[48:51], v14, s[20:21] nt
	s_add_u32 s20, s20, 0x6000
	s_addc_u32 s21, s21, 0
	global_load_dwordx4 v[52:55], v14, s[20:21] nt
	s_add_u32 s20, s20, 0x6000
	s_addc_u32 s21, s21, 0
	global_load_dwordx4 v[56:59], v14, s[20:21] nt
	s_add_u32 s20, s20, 0x6000
	s_addc_u32 s21, s21, 0
	global_load_dwordx4 v[60:63], v14, s[20:21] nt
	s_add_u32 s20, s20, 0x6000
	s_addc_u32 s21, s21, 0
	global_load_dwordx4 v[64:67], v14, s[20:21] nt
	s_add_u32 s20, s20, 0x6000
	s_addc_u32 s21, s21, 0
	global_load_dwordx4 v[68:71], v14, s[20:21] nt
	s_add_u32 s20, s20, 0x6000
	s_addc_u32 s21, s21, 0
	global_load_dwordx4 v[72:75], v14, s[20:21] nt
	s_add_u32 s20, s20, 0x6000
	s_addc_u32 s21, s21, 0
	global_load_dwordx4 v[76:79], v14, s[20:21] nt
	s_add_u32 s20, s20, 0x6000
	s_addc_u32 s21, s21, 0
	global_load_dwordx4 v[196:199], v14, s[20:21] nt
	s_add_u32 s20, s20, 0x6000
	s_addc_u32 s21, s21, 0
	global_load_dwordx4 v[200:203], v14, s[20:21] nt
	s_add_u32 s20, s20, 0x6000
	s_addc_u32 s21, s21, 0
	global_load_dwordx4 v[204:207], v14, s[20:21] nt
	s_add_u32 s20, s20, 0x6000
	s_addc_u32 s21, s21, 0
	global_load_dwordx4 v[208:211], v14, s[20:21] nt
	s_add_u32 s20, s20, 0x6000
	s_addc_u32 s21, s21, 0
	global_load_dwordx4 v[212:215], v14, s[20:21] nt
	s_add_u32 s20, s20, 0x6000
	s_addc_u32 s21, s21, 0
	global_load_dwordx4 v[216:219], v14, s[20:21] nt
	s_add_u32 s20, s20, 0x6000
	s_addc_u32 s21, s21, 0
	global_load_dwordx4 v[220:223], v14, s[20:21] nt
	s_add_u32 s20, s20, 0x6000
	s_addc_u32 s21, s21, 0
	global_load_dwordx4 v[224:227], v14, s[20:21] nt
	s_add_u32 s20, s20, 0x6000
	s_addc_u32 s21, s21, 0
	global_load_dwordx4 v[228:231], v14, s[20:21] nt
	s_add_u32 s20, s20, 0x6000
	s_addc_u32 s21, s21, 0
	global_load_dwordx4 v[96:99], v14, s[20:21] nt
	s_add_u32 s20, s20, 0x6000
	s_addc_u32 s21, s21, 0
	ds_read_b128 v[80:83], v11 offset:0
	ds_read_b128 v[84:87], v11 offset:16
	ds_read_b128 v[88:91], v11 offset:32
	ds_read_b128 v[92:95], v11 offset:48
	ds_read_b128 v[120:123], v11 offset:4096
	ds_read_b128 v[124:127], v11 offset:4112
	ds_read_b128 v[128:131], v11 offset:4128
	ds_read_b128 v[132:135], v11 offset:4144
	ds_read_b128 v[136:139], v11 offset:8192
	ds_read_b128 v[140:143], v11 offset:8208
	ds_read_b128 v[144:147], v11 offset:8224
	ds_read_b128 v[148:151], v11 offset:8240
	ds_read_b128 v[152:155], v11 offset:12288
	ds_read_b128 v[156:159], v11 offset:12304
	ds_read_b128 v[160:163], v11 offset:12320
	ds_read_b128 v[164:167], v11 offset:12336
	ds_read_b128 v[180:183], v11 offset:16384
	ds_read_b128 v[184:187], v11 offset:16400
	ds_read_b128 v[188:191], v11 offset:16416
	ds_read_b128 v[192:195], v11 offset:16432
	s_waitcnt lgkmcnt(0)
	s_waitcnt vmcnt(25)
	v_fmac_f32_e32 v100, v16, v80
	v_fmac_f32_e32 v101, v17, v80
	v_fmac_f32_e32 v102, v18, v80
	v_fmac_f32_e32 v103, v19, v80
	v_fmac_f32_e32 v104, v16, v120
	v_fmac_f32_e32 v105, v17, v120
	v_fmac_f32_e32 v106, v18, v120
	v_fmac_f32_e32 v107, v19, v120
	v_fmac_f32_e32 v108, v16, v136
	v_fmac_f32_e32 v109, v17, v136
	v_fmac_f32_e32 v110, v18, v136
	v_fmac_f32_e32 v111, v19, v136
	v_fmac_f32_e32 v112, v16, v152
	v_fmac_f32_e32 v113, v17, v152
	v_fmac_f32_e32 v114, v18, v152
	v_fmac_f32_e32 v115, v19, v152
	v_fmac_f32_e32 v116, v16, v180
	v_fmac_f32_e32 v117, v17, v180
	v_fmac_f32_e32 v118, v18, v180
	v_fmac_f32_e32 v119, v19, v180
	s_waitcnt vmcnt(24)
	v_fmac_f32_e32 v100, v20, v81
	v_fmac_f32_e32 v101, v21, v81
	v_fmac_f32_e32 v102, v22, v81
	v_fmac_f32_e32 v103, v23, v81
	v_fmac_f32_e32 v104, v20, v121
	v_fmac_f32_e32 v105, v21, v121
	v_fmac_f32_e32 v106, v22, v121
	v_fmac_f32_e32 v107, v23, v121
	v_fmac_f32_e32 v108, v20, v137
	v_fmac_f32_e32 v109, v21, v137
	v_fmac_f32_e32 v110, v22, v137
	v_fmac_f32_e32 v111, v23, v137
	v_fmac_f32_e32 v112, v20, v153
	v_fmac_f32_e32 v113, v21, v153
	v_fmac_f32_e32 v114, v22, v153
	v_fmac_f32_e32 v115, v23, v153
	v_fmac_f32_e32 v116, v20, v181
	v_fmac_f32_e32 v117, v21, v181
	v_fmac_f32_e32 v118, v22, v181
	v_fmac_f32_e32 v119, v23, v181
	s_waitcnt vmcnt(23)
	v_fmac_f32_e32 v100, v24, v82
	v_fmac_f32_e32 v101, v25, v82
	v_fmac_f32_e32 v102, v26, v82
	v_fmac_f32_e32 v103, v27, v82
	v_fmac_f32_e32 v104, v24, v122
	v_fmac_f32_e32 v105, v25, v122
	v_fmac_f32_e32 v106, v26, v122
	v_fmac_f32_e32 v107, v27, v122
	v_fmac_f32_e32 v108, v24, v138
	v_fmac_f32_e32 v109, v25, v138
	v_fmac_f32_e32 v110, v26, v138
	v_fmac_f32_e32 v111, v27, v138
	v_fmac_f32_e32 v112, v24, v154
	v_fmac_f32_e32 v113, v25, v154
	v_fmac_f32_e32 v114, v26, v154
	v_fmac_f32_e32 v115, v27, v154
	v_fmac_f32_e32 v116, v24, v182
	v_fmac_f32_e32 v117, v25, v182
	v_fmac_f32_e32 v118, v26, v182
	v_fmac_f32_e32 v119, v27, v182
	s_waitcnt vmcnt(22)
	v_fmac_f32_e32 v100, v28, v83
	v_fmac_f32_e32 v101, v29, v83
	v_fmac_f32_e32 v102, v30, v83
	v_fmac_f32_e32 v103, v31, v83
	v_fmac_f32_e32 v104, v28, v123
	v_fmac_f32_e32 v105, v29, v123
	v_fmac_f32_e32 v106, v30, v123
	v_fmac_f32_e32 v107, v31, v123
	v_fmac_f32_e32 v108, v28, v139
	v_fmac_f32_e32 v109, v29, v139
	v_fmac_f32_e32 v110, v30, v139
	v_fmac_f32_e32 v111, v31, v139
	v_fmac_f32_e32 v112, v28, v155
	v_fmac_f32_e32 v113, v29, v155
	v_fmac_f32_e32 v114, v30, v155
	v_fmac_f32_e32 v115, v31, v155
	v_fmac_f32_e32 v116, v28, v183
	v_fmac_f32_e32 v117, v29, v183
	v_fmac_f32_e32 v118, v30, v183
	v_fmac_f32_e32 v119, v31, v183
	s_waitcnt vmcnt(21)
	v_fmac_f32_e32 v100, v32, v84
	v_fmac_f32_e32 v101, v33, v84
	v_fmac_f32_e32 v102, v34, v84
	v_fmac_f32_e32 v103, v35, v84
	v_fmac_f32_e32 v104, v32, v124
	v_fmac_f32_e32 v105, v33, v124
	v_fmac_f32_e32 v106, v34, v124
	v_fmac_f32_e32 v107, v35, v124
	v_fmac_f32_e32 v108, v32, v140
	v_fmac_f32_e32 v109, v33, v140
	v_fmac_f32_e32 v110, v34, v140
	v_fmac_f32_e32 v111, v35, v140
	v_fmac_f32_e32 v112, v32, v156
	v_fmac_f32_e32 v113, v33, v156
	v_fmac_f32_e32 v114, v34, v156
	v_fmac_f32_e32 v115, v35, v156
	v_fmac_f32_e32 v116, v32, v184
	v_fmac_f32_e32 v117, v33, v184
	v_fmac_f32_e32 v118, v34, v184
	v_fmac_f32_e32 v119, v35, v184
	s_waitcnt vmcnt(20)
	v_fmac_f32_e32 v100, v36, v85
	v_fmac_f32_e32 v101, v37, v85
	v_fmac_f32_e32 v102, v38, v85
	v_fmac_f32_e32 v103, v39, v85
	v_fmac_f32_e32 v104, v36, v125
	v_fmac_f32_e32 v105, v37, v125
	v_fmac_f32_e32 v106, v38, v125
	v_fmac_f32_e32 v107, v39, v125
	v_fmac_f32_e32 v108, v36, v141
	v_fmac_f32_e32 v109, v37, v141
	v_fmac_f32_e32 v110, v38, v141
	v_fmac_f32_e32 v111, v39, v141
	v_fmac_f32_e32 v112, v36, v157
	v_fmac_f32_e32 v113, v37, v157
	v_fmac_f32_e32 v114, v38, v157
	v_fmac_f32_e32 v115, v39, v157
	v_fmac_f32_e32 v116, v36, v185
	v_fmac_f32_e32 v117, v37, v185
	v_fmac_f32_e32 v118, v38, v185
	v_fmac_f32_e32 v119, v39, v185
	s_waitcnt vmcnt(19)
	v_fmac_f32_e32 v100, v40, v86
	v_fmac_f32_e32 v101, v41, v86
	v_fmac_f32_e32 v102, v42, v86
	v_fmac_f32_e32 v103, v43, v86
	v_fmac_f32_e32 v104, v40, v126
	v_fmac_f32_e32 v105, v41, v126
	v_fmac_f32_e32 v106, v42, v126
	v_fmac_f32_e32 v107, v43, v126
	v_fmac_f32_e32 v108, v40, v142
	v_fmac_f32_e32 v109, v41, v142
	v_fmac_f32_e32 v110, v42, v142
	v_fmac_f32_e32 v111, v43, v142
	v_fmac_f32_e32 v112, v40, v158
	v_fmac_f32_e32 v113, v41, v158
	v_fmac_f32_e32 v114, v42, v158
	v_fmac_f32_e32 v115, v43, v158
	v_fmac_f32_e32 v116, v40, v186
	v_fmac_f32_e32 v117, v41, v186
	v_fmac_f32_e32 v118, v42, v186
	v_fmac_f32_e32 v119, v43, v186
	s_waitcnt vmcnt(18)
	v_fmac_f32_e32 v100, v44, v87
	v_fmac_f32_e32 v101, v45, v87
	v_fmac_f32_e32 v102, v46, v87
	v_fmac_f32_e32 v103, v47, v87
	v_fmac_f32_e32 v104, v44, v127
	v_fmac_f32_e32 v105, v45, v127
	v_fmac_f32_e32 v106, v46, v127
	v_fmac_f32_e32 v107, v47, v127
	v_fmac_f32_e32 v108, v44, v143
	v_fmac_f32_e32 v109, v45, v143
	v_fmac_f32_e32 v110, v46, v143
	v_fmac_f32_e32 v111, v47, v143
	v_fmac_f32_e32 v112, v44, v159
	v_fmac_f32_e32 v113, v45, v159
	v_fmac_f32_e32 v114, v46, v159
	v_fmac_f32_e32 v115, v47, v159
	v_fmac_f32_e32 v116, v44, v187
	v_fmac_f32_e32 v117, v45, v187
	v_fmac_f32_e32 v118, v46, v187
	v_fmac_f32_e32 v119, v47, v187
	s_waitcnt vmcnt(17)
	v_fmac_f32_e32 v100, v48, v88
	v_fmac_f32_e32 v101, v49, v88
	v_fmac_f32_e32 v102, v50, v88
	v_fmac_f32_e32 v103, v51, v88
	v_fmac_f32_e32 v104, v48, v128
	v_fmac_f32_e32 v105, v49, v128
	v_fmac_f32_e32 v106, v50, v128
	v_fmac_f32_e32 v107, v51, v128
	v_fmac_f32_e32 v108, v48, v144
	v_fmac_f32_e32 v109, v49, v144
	v_fmac_f32_e32 v110, v50, v144
	v_fmac_f32_e32 v111, v51, v144
	v_fmac_f32_e32 v112, v48, v160
	v_fmac_f32_e32 v113, v49, v160
	v_fmac_f32_e32 v114, v50, v160
	v_fmac_f32_e32 v115, v51, v160
	v_fmac_f32_e32 v116, v48, v188
	v_fmac_f32_e32 v117, v49, v188
	v_fmac_f32_e32 v118, v50, v188
	v_fmac_f32_e32 v119, v51, v188
	s_waitcnt vmcnt(16)
	v_fmac_f32_e32 v100, v52, v89
	v_fmac_f32_e32 v101, v53, v89
	v_fmac_f32_e32 v102, v54, v89
	v_fmac_f32_e32 v103, v55, v89
	v_fmac_f32_e32 v104, v52, v129
	v_fmac_f32_e32 v105, v53, v129
	v_fmac_f32_e32 v106, v54, v129
	v_fmac_f32_e32 v107, v55, v129
	v_fmac_f32_e32 v108, v52, v145
	v_fmac_f32_e32 v109, v53, v145
	v_fmac_f32_e32 v110, v54, v145
	v_fmac_f32_e32 v111, v55, v145
	v_fmac_f32_e32 v112, v52, v161
	v_fmac_f32_e32 v113, v53, v161
	v_fmac_f32_e32 v114, v54, v161
	v_fmac_f32_e32 v115, v55, v161
	v_fmac_f32_e32 v116, v52, v189
	v_fmac_f32_e32 v117, v53, v189
	v_fmac_f32_e32 v118, v54, v189
	v_fmac_f32_e32 v119, v55, v189
	s_waitcnt vmcnt(15)
	v_fmac_f32_e32 v100, v56, v90
	v_fmac_f32_e32 v101, v57, v90
	v_fmac_f32_e32 v102, v58, v90
	v_fmac_f32_e32 v103, v59, v90
	v_fmac_f32_e32 v104, v56, v130
	v_fmac_f32_e32 v105, v57, v130
	v_fmac_f32_e32 v106, v58, v130
	v_fmac_f32_e32 v107, v59, v130
	v_fmac_f32_e32 v108, v56, v146
	v_fmac_f32_e32 v109, v57, v146
	v_fmac_f32_e32 v110, v58, v146
	v_fmac_f32_e32 v111, v59, v146
	v_fmac_f32_e32 v112, v56, v162
	v_fmac_f32_e32 v113, v57, v162
	v_fmac_f32_e32 v114, v58, v162
	v_fmac_f32_e32 v115, v59, v162
	v_fmac_f32_e32 v116, v56, v190
	v_fmac_f32_e32 v117, v57, v190
	v_fmac_f32_e32 v118, v58, v190
	v_fmac_f32_e32 v119, v59, v190
	s_waitcnt vmcnt(14)
	v_fmac_f32_e32 v100, v60, v91
	v_fmac_f32_e32 v101, v61, v91
	v_fmac_f32_e32 v102, v62, v91
	v_fmac_f32_e32 v103, v63, v91
	v_fmac_f32_e32 v104, v60, v131
	v_fmac_f32_e32 v105, v61, v131
	v_fmac_f32_e32 v106, v62, v131
	v_fmac_f32_e32 v107, v63, v131
	v_fmac_f32_e32 v108, v60, v147
	v_fmac_f32_e32 v109, v61, v147
	v_fmac_f32_e32 v110, v62, v147
	v_fmac_f32_e32 v111, v63, v147
	v_fmac_f32_e32 v112, v60, v163
	v_fmac_f32_e32 v113, v61, v163
	v_fmac_f32_e32 v114, v62, v163
	v_fmac_f32_e32 v115, v63, v163
	v_fmac_f32_e32 v116, v60, v191
	v_fmac_f32_e32 v117, v61, v191
	v_fmac_f32_e32 v118, v62, v191
	v_fmac_f32_e32 v119, v63, v191
	s_waitcnt vmcnt(13)
	v_fmac_f32_e32 v100, v64, v92
	v_fmac_f32_e32 v101, v65, v92
	v_fmac_f32_e32 v102, v66, v92
	v_fmac_f32_e32 v103, v67, v92
	v_fmac_f32_e32 v104, v64, v132
	v_fmac_f32_e32 v105, v65, v132
	v_fmac_f32_e32 v106, v66, v132
	v_fmac_f32_e32 v107, v67, v132
	v_fmac_f32_e32 v108, v64, v148
	v_fmac_f32_e32 v109, v65, v148
	v_fmac_f32_e32 v110, v66, v148
	v_fmac_f32_e32 v111, v67, v148
	v_fmac_f32_e32 v112, v64, v164
	v_fmac_f32_e32 v113, v65, v164
	v_fmac_f32_e32 v114, v66, v164
	v_fmac_f32_e32 v115, v67, v164
	v_fmac_f32_e32 v116, v64, v192
	v_fmac_f32_e32 v117, v65, v192
	v_fmac_f32_e32 v118, v66, v192
	v_fmac_f32_e32 v119, v67, v192
	s_waitcnt vmcnt(12)
	v_fmac_f32_e32 v100, v68, v93
	v_fmac_f32_e32 v101, v69, v93
	v_fmac_f32_e32 v102, v70, v93
	v_fmac_f32_e32 v103, v71, v93
	v_fmac_f32_e32 v104, v68, v133
	v_fmac_f32_e32 v105, v69, v133
	v_fmac_f32_e32 v106, v70, v133
	v_fmac_f32_e32 v107, v71, v133
	v_fmac_f32_e32 v108, v68, v149
	v_fmac_f32_e32 v109, v69, v149
	v_fmac_f32_e32 v110, v70, v149
	v_fmac_f32_e32 v111, v71, v149
	v_fmac_f32_e32 v112, v68, v165
	v_fmac_f32_e32 v113, v69, v165
	v_fmac_f32_e32 v114, v70, v165
	v_fmac_f32_e32 v115, v71, v165
	v_fmac_f32_e32 v116, v68, v193
	v_fmac_f32_e32 v117, v69, v193
	v_fmac_f32_e32 v118, v70, v193
	v_fmac_f32_e32 v119, v71, v193
	s_waitcnt vmcnt(11)
	v_fmac_f32_e32 v100, v72, v94
	v_fmac_f32_e32 v101, v73, v94
	v_fmac_f32_e32 v102, v74, v94
	v_fmac_f32_e32 v103, v75, v94
	v_fmac_f32_e32 v104, v72, v134
	v_fmac_f32_e32 v105, v73, v134
	v_fmac_f32_e32 v106, v74, v134
	v_fmac_f32_e32 v107, v75, v134
	v_fmac_f32_e32 v108, v72, v150
	v_fmac_f32_e32 v109, v73, v150
	v_fmac_f32_e32 v110, v74, v150
	v_fmac_f32_e32 v111, v75, v150
	v_fmac_f32_e32 v112, v72, v166
	v_fmac_f32_e32 v113, v73, v166
	v_fmac_f32_e32 v114, v74, v166
	v_fmac_f32_e32 v115, v75, v166
	v_fmac_f32_e32 v116, v72, v194
	v_fmac_f32_e32 v117, v73, v194
	v_fmac_f32_e32 v118, v74, v194
	v_fmac_f32_e32 v119, v75, v194
	s_waitcnt vmcnt(10)
	v_fmac_f32_e32 v100, v76, v95
	v_fmac_f32_e32 v101, v77, v95
	v_fmac_f32_e32 v102, v78, v95
	v_fmac_f32_e32 v103, v79, v95
	v_fmac_f32_e32 v104, v76, v135
	v_fmac_f32_e32 v105, v77, v135
	v_fmac_f32_e32 v106, v78, v135
	v_fmac_f32_e32 v107, v79, v135
	v_fmac_f32_e32 v108, v76, v151
	v_fmac_f32_e32 v109, v77, v151
	v_fmac_f32_e32 v110, v78, v151
	v_fmac_f32_e32 v111, v79, v151
	v_fmac_f32_e32 v112, v76, v167
	v_fmac_f32_e32 v113, v77, v167
	v_fmac_f32_e32 v114, v78, v167
	v_fmac_f32_e32 v115, v79, v167
	v_fmac_f32_e32 v116, v76, v195
	v_fmac_f32_e32 v117, v77, v195
	v_fmac_f32_e32 v118, v78, v195
	v_fmac_f32_e32 v119, v79, v195
	global_load_dwordx4 v[16:19], v14, s[20:21] nt
	s_add_u32 s20, s20, 0x6000
	s_addc_u32 s21, s21, 0
	global_load_dwordx4 v[20:23], v14, s[20:21] nt
	s_add_u32 s20, s20, 0x6000
	s_addc_u32 s21, s21, 0
	global_load_dwordx4 v[24:27], v14, s[20:21] nt
	s_add_u32 s20, s20, 0x6000
	s_addc_u32 s21, s21, 0
	global_load_dwordx4 v[28:31], v14, s[20:21] nt
	s_add_u32 s20, s20, 0x6000
	s_addc_u32 s21, s21, 0
	global_load_dwordx4 v[32:35], v14, s[20:21] nt
	s_add_u32 s20, s20, 0x6000
	s_addc_u32 s21, s21, 0
	global_load_dwordx4 v[36:39], v14, s[20:21] nt
	s_add_u32 s20, s20, 0x6000
	s_addc_u32 s21, s21, 0
	ds_read_b128 v[80:83], v11 offset:64
	ds_read_b128 v[84:87], v11 offset:80
	ds_read_b128 v[88:91], v11 offset:96
	ds_read_b128 v[92:95], v11 offset:112
	ds_read_b128 v[120:123], v11 offset:4160
	ds_read_b128 v[124:127], v11 offset:4176
	ds_read_b128 v[128:131], v11 offset:4192
	ds_read_b128 v[132:135], v11 offset:4208
	ds_read_b128 v[136:139], v11 offset:8256
	ds_read_b128 v[140:143], v11 offset:8272
	ds_read_b128 v[144:147], v11 offset:8288
	ds_read_b128 v[148:151], v11 offset:8304
	ds_read_b128 v[152:155], v11 offset:12352
	ds_read_b128 v[156:159], v11 offset:12368
	ds_read_b128 v[160:163], v11 offset:12384
	ds_read_b128 v[164:167], v11 offset:12400
	ds_read_b128 v[180:183], v11 offset:16448
	ds_read_b128 v[184:187], v11 offset:16464
	ds_read_b128 v[188:191], v11 offset:16480
	ds_read_b128 v[192:195], v11 offset:16496
	s_waitcnt lgkmcnt(0)
	s_waitcnt vmcnt(15)
	v_fmac_f32_e32 v100, v196, v80
	v_fmac_f32_e32 v101, v197, v80
	v_fmac_f32_e32 v102, v198, v80
	v_fmac_f32_e32 v103, v199, v80
	v_fmac_f32_e32 v104, v196, v120
	v_fmac_f32_e32 v105, v197, v120
	v_fmac_f32_e32 v106, v198, v120
	v_fmac_f32_e32 v107, v199, v120
	v_fmac_f32_e32 v108, v196, v136
	v_fmac_f32_e32 v109, v197, v136
	v_fmac_f32_e32 v110, v198, v136
	v_fmac_f32_e32 v111, v199, v136
	v_fmac_f32_e32 v112, v196, v152
	v_fmac_f32_e32 v113, v197, v152
	v_fmac_f32_e32 v114, v198, v152
	v_fmac_f32_e32 v115, v199, v152
	v_fmac_f32_e32 v116, v196, v180
	v_fmac_f32_e32 v117, v197, v180
	v_fmac_f32_e32 v118, v198, v180
	v_fmac_f32_e32 v119, v199, v180
	s_waitcnt vmcnt(14)
	v_fmac_f32_e32 v100, v200, v81
	v_fmac_f32_e32 v101, v201, v81
	v_fmac_f32_e32 v102, v202, v81
	v_fmac_f32_e32 v103, v203, v81
	v_fmac_f32_e32 v104, v200, v121
	v_fmac_f32_e32 v105, v201, v121
	v_fmac_f32_e32 v106, v202, v121
	v_fmac_f32_e32 v107, v203, v121
	v_fmac_f32_e32 v108, v200, v137
	v_fmac_f32_e32 v109, v201, v137
	v_fmac_f32_e32 v110, v202, v137
	v_fmac_f32_e32 v111, v203, v137
	v_fmac_f32_e32 v112, v200, v153
	v_fmac_f32_e32 v113, v201, v153
	v_fmac_f32_e32 v114, v202, v153
	v_fmac_f32_e32 v115, v203, v153
	v_fmac_f32_e32 v116, v200, v181
	v_fmac_f32_e32 v117, v201, v181
	v_fmac_f32_e32 v118, v202, v181
	v_fmac_f32_e32 v119, v203, v181
	s_waitcnt vmcnt(13)
	v_fmac_f32_e32 v100, v204, v82
	v_fmac_f32_e32 v101, v205, v82
	v_fmac_f32_e32 v102, v206, v82
	v_fmac_f32_e32 v103, v207, v82
	v_fmac_f32_e32 v104, v204, v122
	v_fmac_f32_e32 v105, v205, v122
	v_fmac_f32_e32 v106, v206, v122
	v_fmac_f32_e32 v107, v207, v122
	v_fmac_f32_e32 v108, v204, v138
	v_fmac_f32_e32 v109, v205, v138
	v_fmac_f32_e32 v110, v206, v138
	v_fmac_f32_e32 v111, v207, v138
	v_fmac_f32_e32 v112, v204, v154
	v_fmac_f32_e32 v113, v205, v154
	v_fmac_f32_e32 v114, v206, v154
	v_fmac_f32_e32 v115, v207, v154
	v_fmac_f32_e32 v116, v204, v182
	v_fmac_f32_e32 v117, v205, v182
	v_fmac_f32_e32 v118, v206, v182
	v_fmac_f32_e32 v119, v207, v182
	s_waitcnt vmcnt(12)
	v_fmac_f32_e32 v100, v208, v83
	v_fmac_f32_e32 v101, v209, v83
	v_fmac_f32_e32 v102, v210, v83
	v_fmac_f32_e32 v103, v211, v83
	v_fmac_f32_e32 v104, v208, v123
	v_fmac_f32_e32 v105, v209, v123
	v_fmac_f32_e32 v106, v210, v123
	v_fmac_f32_e32 v107, v211, v123
	v_fmac_f32_e32 v108, v208, v139
	v_fmac_f32_e32 v109, v209, v139
	v_fmac_f32_e32 v110, v210, v139
	v_fmac_f32_e32 v111, v211, v139
	v_fmac_f32_e32 v112, v208, v155
	v_fmac_f32_e32 v113, v209, v155
	v_fmac_f32_e32 v114, v210, v155
	v_fmac_f32_e32 v115, v211, v155
	v_fmac_f32_e32 v116, v208, v183
	v_fmac_f32_e32 v117, v209, v183
	v_fmac_f32_e32 v118, v210, v183
	v_fmac_f32_e32 v119, v211, v183
	s_waitcnt vmcnt(11)
	v_fmac_f32_e32 v100, v212, v84
	v_fmac_f32_e32 v101, v213, v84
	v_fmac_f32_e32 v102, v214, v84
	v_fmac_f32_e32 v103, v215, v84
	v_fmac_f32_e32 v104, v212, v124
	v_fmac_f32_e32 v105, v213, v124
	v_fmac_f32_e32 v106, v214, v124
	v_fmac_f32_e32 v107, v215, v124
	v_fmac_f32_e32 v108, v212, v140
	v_fmac_f32_e32 v109, v213, v140
	v_fmac_f32_e32 v110, v214, v140
	v_fmac_f32_e32 v111, v215, v140
	v_fmac_f32_e32 v112, v212, v156
	v_fmac_f32_e32 v113, v213, v156
	v_fmac_f32_e32 v114, v214, v156
	v_fmac_f32_e32 v115, v215, v156
	v_fmac_f32_e32 v116, v212, v184
	v_fmac_f32_e32 v117, v213, v184
	v_fmac_f32_e32 v118, v214, v184
	v_fmac_f32_e32 v119, v215, v184
	s_waitcnt vmcnt(10)
	v_fmac_f32_e32 v100, v216, v85
	v_fmac_f32_e32 v101, v217, v85
	v_fmac_f32_e32 v102, v218, v85
	v_fmac_f32_e32 v103, v219, v85
	v_fmac_f32_e32 v104, v216, v125
	v_fmac_f32_e32 v105, v217, v125
	v_fmac_f32_e32 v106, v218, v125
	v_fmac_f32_e32 v107, v219, v125
	v_fmac_f32_e32 v108, v216, v141
	v_fmac_f32_e32 v109, v217, v141
	v_fmac_f32_e32 v110, v218, v141
	v_fmac_f32_e32 v111, v219, v141
	v_fmac_f32_e32 v112, v216, v157
	v_fmac_f32_e32 v113, v217, v157
	v_fmac_f32_e32 v114, v218, v157
	v_fmac_f32_e32 v115, v219, v157
	v_fmac_f32_e32 v116, v216, v185
	v_fmac_f32_e32 v117, v217, v185
	v_fmac_f32_e32 v118, v218, v185
	v_fmac_f32_e32 v119, v219, v185
	s_waitcnt vmcnt(9)
	v_fmac_f32_e32 v100, v220, v86
	v_fmac_f32_e32 v101, v221, v86
	v_fmac_f32_e32 v102, v222, v86
	v_fmac_f32_e32 v103, v223, v86
	v_fmac_f32_e32 v104, v220, v126
	v_fmac_f32_e32 v105, v221, v126
	v_fmac_f32_e32 v106, v222, v126
	v_fmac_f32_e32 v107, v223, v126
	v_fmac_f32_e32 v108, v220, v142
	v_fmac_f32_e32 v109, v221, v142
	v_fmac_f32_e32 v110, v222, v142
	v_fmac_f32_e32 v111, v223, v142
	v_fmac_f32_e32 v112, v220, v158
	v_fmac_f32_e32 v113, v221, v158
	v_fmac_f32_e32 v114, v222, v158
	v_fmac_f32_e32 v115, v223, v158
	v_fmac_f32_e32 v116, v220, v186
	v_fmac_f32_e32 v117, v221, v186
	v_fmac_f32_e32 v118, v222, v186
	v_fmac_f32_e32 v119, v223, v186
	s_waitcnt vmcnt(8)
	v_fmac_f32_e32 v100, v224, v87
	v_fmac_f32_e32 v101, v225, v87
	v_fmac_f32_e32 v102, v226, v87
	v_fmac_f32_e32 v103, v227, v87
	v_fmac_f32_e32 v104, v224, v127
	v_fmac_f32_e32 v105, v225, v127
	v_fmac_f32_e32 v106, v226, v127
	v_fmac_f32_e32 v107, v227, v127
	v_fmac_f32_e32 v108, v224, v143
	v_fmac_f32_e32 v109, v225, v143
	v_fmac_f32_e32 v110, v226, v143
	v_fmac_f32_e32 v111, v227, v143
	v_fmac_f32_e32 v112, v224, v159
	v_fmac_f32_e32 v113, v225, v159
	v_fmac_f32_e32 v114, v226, v159
	v_fmac_f32_e32 v115, v227, v159
	v_fmac_f32_e32 v116, v224, v187
	v_fmac_f32_e32 v117, v225, v187
	v_fmac_f32_e32 v118, v226, v187
	v_fmac_f32_e32 v119, v227, v187
	s_waitcnt vmcnt(7)
	v_fmac_f32_e32 v100, v228, v88
	v_fmac_f32_e32 v101, v229, v88
	v_fmac_f32_e32 v102, v230, v88
	v_fmac_f32_e32 v103, v231, v88
	v_fmac_f32_e32 v104, v228, v128
	v_fmac_f32_e32 v105, v229, v128
	v_fmac_f32_e32 v106, v230, v128
	v_fmac_f32_e32 v107, v231, v128
	v_fmac_f32_e32 v108, v228, v144
	v_fmac_f32_e32 v109, v229, v144
	v_fmac_f32_e32 v110, v230, v144
	v_fmac_f32_e32 v111, v231, v144
	v_fmac_f32_e32 v112, v228, v160
	v_fmac_f32_e32 v113, v229, v160
	v_fmac_f32_e32 v114, v230, v160
	v_fmac_f32_e32 v115, v231, v160
	v_fmac_f32_e32 v116, v228, v188
	v_fmac_f32_e32 v117, v229, v188
	v_fmac_f32_e32 v118, v230, v188
	v_fmac_f32_e32 v119, v231, v188
	s_waitcnt vmcnt(6)
	v_fmac_f32_e32 v100, v96, v89
	v_fmac_f32_e32 v101, v97, v89
	v_fmac_f32_e32 v102, v98, v89
	v_fmac_f32_e32 v103, v99, v89
	v_fmac_f32_e32 v104, v96, v129
	v_fmac_f32_e32 v105, v97, v129
	v_fmac_f32_e32 v106, v98, v129
	v_fmac_f32_e32 v107, v99, v129
	v_fmac_f32_e32 v108, v96, v145
	v_fmac_f32_e32 v109, v97, v145
	v_fmac_f32_e32 v110, v98, v145
	v_fmac_f32_e32 v111, v99, v145
	v_fmac_f32_e32 v112, v96, v161
	v_fmac_f32_e32 v113, v97, v161
	v_fmac_f32_e32 v114, v98, v161
	v_fmac_f32_e32 v115, v99, v161
	v_fmac_f32_e32 v116, v96, v189
	v_fmac_f32_e32 v117, v97, v189
	v_fmac_f32_e32 v118, v98, v189
	v_fmac_f32_e32 v119, v99, v189
	s_waitcnt vmcnt(5)
	v_fmac_f32_e32 v100, v16, v90
	v_fmac_f32_e32 v101, v17, v90
	v_fmac_f32_e32 v102, v18, v90
	v_fmac_f32_e32 v103, v19, v90
	v_fmac_f32_e32 v104, v16, v130
	v_fmac_f32_e32 v105, v17, v130
	v_fmac_f32_e32 v106, v18, v130
	v_fmac_f32_e32 v107, v19, v130
	v_fmac_f32_e32 v108, v16, v146
	v_fmac_f32_e32 v109, v17, v146
	v_fmac_f32_e32 v110, v18, v146
	v_fmac_f32_e32 v111, v19, v146
	v_fmac_f32_e32 v112, v16, v162
	v_fmac_f32_e32 v113, v17, v162
	v_fmac_f32_e32 v114, v18, v162
	v_fmac_f32_e32 v115, v19, v162
	v_fmac_f32_e32 v116, v16, v190
	v_fmac_f32_e32 v117, v17, v190
	v_fmac_f32_e32 v118, v18, v190
	v_fmac_f32_e32 v119, v19, v190
	s_waitcnt vmcnt(4)
	v_fmac_f32_e32 v100, v20, v91
	v_fmac_f32_e32 v101, v21, v91
	v_fmac_f32_e32 v102, v22, v91
	v_fmac_f32_e32 v103, v23, v91
	v_fmac_f32_e32 v104, v20, v131
	v_fmac_f32_e32 v105, v21, v131
	v_fmac_f32_e32 v106, v22, v131
	v_fmac_f32_e32 v107, v23, v131
	v_fmac_f32_e32 v108, v20, v147
	v_fmac_f32_e32 v109, v21, v147
	v_fmac_f32_e32 v110, v22, v147
	v_fmac_f32_e32 v111, v23, v147
	v_fmac_f32_e32 v112, v20, v163
	v_fmac_f32_e32 v113, v21, v163
	v_fmac_f32_e32 v114, v22, v163
	v_fmac_f32_e32 v115, v23, v163
	v_fmac_f32_e32 v116, v20, v191
	v_fmac_f32_e32 v117, v21, v191
	v_fmac_f32_e32 v118, v22, v191
	v_fmac_f32_e32 v119, v23, v191
	s_waitcnt vmcnt(3)
	v_fmac_f32_e32 v100, v24, v92
	v_fmac_f32_e32 v101, v25, v92
	v_fmac_f32_e32 v102, v26, v92
	v_fmac_f32_e32 v103, v27, v92
	v_fmac_f32_e32 v104, v24, v132
	v_fmac_f32_e32 v105, v25, v132
	v_fmac_f32_e32 v106, v26, v132
	v_fmac_f32_e32 v107, v27, v132
	v_fmac_f32_e32 v108, v24, v148
	v_fmac_f32_e32 v109, v25, v148
	v_fmac_f32_e32 v110, v26, v148
	v_fmac_f32_e32 v111, v27, v148
	v_fmac_f32_e32 v112, v24, v164
	v_fmac_f32_e32 v113, v25, v164
	v_fmac_f32_e32 v114, v26, v164
	v_fmac_f32_e32 v115, v27, v164
	v_fmac_f32_e32 v116, v24, v192
	v_fmac_f32_e32 v117, v25, v192
	v_fmac_f32_e32 v118, v26, v192
	v_fmac_f32_e32 v119, v27, v192
	s_waitcnt vmcnt(2)
	v_fmac_f32_e32 v100, v28, v93
	v_fmac_f32_e32 v101, v29, v93
	v_fmac_f32_e32 v102, v30, v93
	v_fmac_f32_e32 v103, v31, v93
	v_fmac_f32_e32 v104, v28, v133
	v_fmac_f32_e32 v105, v29, v133
	v_fmac_f32_e32 v106, v30, v133
	v_fmac_f32_e32 v107, v31, v133
	v_fmac_f32_e32 v108, v28, v149
	v_fmac_f32_e32 v109, v29, v149
	v_fmac_f32_e32 v110, v30, v149
	v_fmac_f32_e32 v111, v31, v149
	v_fmac_f32_e32 v112, v28, v165
	v_fmac_f32_e32 v113, v29, v165
	v_fmac_f32_e32 v114, v30, v165
	v_fmac_f32_e32 v115, v31, v165
	v_fmac_f32_e32 v116, v28, v193
	v_fmac_f32_e32 v117, v29, v193
	v_fmac_f32_e32 v118, v30, v193
	v_fmac_f32_e32 v119, v31, v193
	s_waitcnt vmcnt(1)
	v_fmac_f32_e32 v100, v32, v94
	v_fmac_f32_e32 v101, v33, v94
	v_fmac_f32_e32 v102, v34, v94
	v_fmac_f32_e32 v103, v35, v94
	v_fmac_f32_e32 v104, v32, v134
	v_fmac_f32_e32 v105, v33, v134
	v_fmac_f32_e32 v106, v34, v134
	v_fmac_f32_e32 v107, v35, v134
	v_fmac_f32_e32 v108, v32, v150
	v_fmac_f32_e32 v109, v33, v150
	v_fmac_f32_e32 v110, v34, v150
	v_fmac_f32_e32 v111, v35, v150
	v_fmac_f32_e32 v112, v32, v166
	v_fmac_f32_e32 v113, v33, v166
	v_fmac_f32_e32 v114, v34, v166
	v_fmac_f32_e32 v115, v35, v166
	v_fmac_f32_e32 v116, v32, v194
	v_fmac_f32_e32 v117, v33, v194
	v_fmac_f32_e32 v118, v34, v194
	v_fmac_f32_e32 v119, v35, v194
	s_waitcnt vmcnt(0)
	v_fmac_f32_e32 v100, v36, v95
	v_fmac_f32_e32 v101, v37, v95
	v_fmac_f32_e32 v102, v38, v95
	v_fmac_f32_e32 v103, v39, v95
	v_fmac_f32_e32 v104, v36, v135
	v_fmac_f32_e32 v105, v37, v135
	v_fmac_f32_e32 v106, v38, v135
	v_fmac_f32_e32 v107, v39, v135
	v_fmac_f32_e32 v108, v36, v151
	v_fmac_f32_e32 v109, v37, v151
	v_fmac_f32_e32 v110, v38, v151
	v_fmac_f32_e32 v111, v39, v151
	v_fmac_f32_e32 v112, v36, v167
	v_fmac_f32_e32 v113, v37, v167
	v_fmac_f32_e32 v114, v38, v167
	v_fmac_f32_e32 v115, v39, v167
	v_fmac_f32_e32 v116, v36, v195
	v_fmac_f32_e32 v117, v37, v195
	v_fmac_f32_e32 v118, v38, v195
	v_fmac_f32_e32 v119, v39, v195
	v_lshl_add_u32 v11, s16, 2, v13
	v_mul_u32_u24_e32 v11, 0x500, v11
	v_lshl_add_u32 v11, v12, 4, v11
	ds_write_b128 v11, v[100:103] offset:20480
	ds_write_b128 v11, v[104:107] offset:20736
	ds_write_b128 v11, v[108:111] offset:20992
	ds_write_b128 v11, v[112:115] offset:21248
	ds_write_b128 v11, v[116:119] offset:21504
	s_waitcnt lgkmcnt(0)
	s_barrier
	v_cmp_gt_u32_e32 vcc, 0x140, v1
	s_and_saveexec_b64 s[16:17], vcc
	s_cbranch_execz .Lgv_fin
	v_and_b32_e32 v12, 63, v1
	v_lshrrev_b32_e32 v13, 6, v1
	v_add_u32_e32 v14, s15, v12
	s_mul_i32 s20, s14, 0x1800
	v_add_u32_e32 v2, s20, v14
	v_lshlrev_b32_e32 v2, 2, v2
	global_load_dword v3, v2, s[34:35]
	v_lshlrev_b32_e32 v11, 8, v13
	v_lshl_add_u32 v11, v12, 2, v11
	ds_read_b32 v16, v11 offset:20480
	ds_read_b32 v17, v11 offset:21760
	ds_read_b32 v18, v11 offset:23040
	ds_read_b32 v19, v11 offset:24320
	ds_read_b32 v20, v11 offset:25600
	ds_read_b32 v21, v11 offset:26880
	ds_read_b32 v22, v11 offset:28160
	ds_read_b32 v23, v11 offset:29440
	ds_read_b32 v24, v11 offset:30720
	ds_read_b32 v25, v11 offset:32000
	ds_read_b32 v26, v11 offset:33280
	ds_read_b32 v27, v11 offset:34560
	ds_read_b32 v28, v11 offset:35840
	ds_read_b32 v29, v11 offset:37120
	ds_read_b32 v30, v11 offset:38400
	ds_read_b32 v31, v11 offset:39680
	ds_read_b32 v32, v11 offset:40960
	ds_read_b32 v33, v11 offset:42240
	ds_read_b32 v34, v11 offset:43520
	ds_read_b32 v35, v11 offset:44800
	ds_read_b32 v36, v11 offset:46080
	ds_read_b32 v37, v11 offset:47360
	ds_read_b32 v38, v11 offset:48640
	ds_read_b32 v39, v11 offset:49920
	ds_read_b32 v40, v11 offset:51200
	ds_read_b32 v41, v11 offset:52480
	ds_read_b32 v42, v11 offset:53760
	ds_read_b32 v43, v11 offset:55040
	ds_read_b32 v44, v11 offset:56320
	ds_read_b32 v45, v11 offset:57600
	ds_read_b32 v46, v11 offset:58880
	ds_read_b32 v47, v11 offset:60160
	s_waitcnt vmcnt(0)
	s_waitcnt lgkmcnt(15)
	v_add_f32_e32 v3, v3, v16
	s_waitcnt lgkmcnt(15)
	v_add_f32_e32 v3, v3, v17
	s_waitcnt lgkmcnt(15)
	v_add_f32_e32 v3, v3, v18
	s_waitcnt lgkmcnt(15)
	v_add_f32_e32 v3, v3, v19
	s_waitcnt lgkmcnt(15)
	v_add_f32_e32 v3, v3, v20
	s_waitcnt lgkmcnt(15)
	v_add_f32_e32 v3, v3, v21
	s_waitcnt lgkmcnt(15)
	v_add_f32_e32 v3, v3, v22
	s_waitcnt lgkmcnt(15)
	v_add_f32_e32 v3, v3, v23
	s_waitcnt lgkmcnt(15)
	v_add_f32_e32 v3, v3, v24
	s_waitcnt lgkmcnt(15)
	v_add_f32_e32 v3, v3, v25
	s_waitcnt lgkmcnt(15)
	v_add_f32_e32 v3, v3, v26
	s_waitcnt lgkmcnt(15)
	v_add_f32_e32 v3, v3, v27
	s_waitcnt lgkmcnt(15)
	v_add_f32_e32 v3, v3, v28
	s_waitcnt lgkmcnt(15)
	v_add_f32_e32 v3, v3, v29
	s_waitcnt lgkmcnt(15)
	v_add_f32_e32 v3, v3, v30
	s_waitcnt lgkmcnt(15)
	v_add_f32_e32 v3, v3, v31
	s_waitcnt lgkmcnt(15)
	v_add_f32_e32 v3, v3, v32
	s_waitcnt lgkmcnt(14)
	v_add_f32_e32 v3, v3, v33
	s_waitcnt lgkmcnt(13)
	v_add_f32_e32 v3, v3, v34
	s_waitcnt lgkmcnt(12)
	v_add_f32_e32 v3, v3, v35
	s_waitcnt lgkmcnt(11)
	v_add_f32_e32 v3, v3, v36
	s_waitcnt lgkmcnt(10)
	v_add_f32_e32 v3, v3, v37
	s_waitcnt lgkmcnt(9)
	v_add_f32_e32 v3, v3, v38
	s_waitcnt lgkmcnt(8)
	v_add_f32_e32 v3, v3, v39
	s_waitcnt lgkmcnt(7)
	v_add_f32_e32 v3, v3, v40
	s_waitcnt lgkmcnt(6)
	v_add_f32_e32 v3, v3, v41
	s_waitcnt lgkmcnt(5)
	v_add_f32_e32 v3, v3, v42
	s_waitcnt lgkmcnt(4)
	v_add_f32_e32 v3, v3, v43
	s_waitcnt lgkmcnt(3)
	v_add_f32_e32 v3, v3, v44
	s_waitcnt lgkmcnt(2)
	v_add_f32_e32 v3, v3, v45
	s_waitcnt lgkmcnt(1)
	v_add_f32_e32 v3, v3, v46
	s_waitcnt lgkmcnt(0)
	v_add_f32_e32 v3, v3, v47
	s_lshr_b32 s20, s15, 10
	v_and_b32_e32 v14, 0x3ff, v14
	s_mul_i32 s21, s14, 5
	v_add_u32_e32 v4, s21, v13
	v_mul_u32_u24_e32 v4, 0x1800, v4
	v_add_u32_e32 v4, v4, v14
	v_lshlrev_b32_e32 v4, 2, v4
	s_add_u32 s26, s10, 0x780000
	s_addc_u32 s27, s11, 0
	s_cmp_lg_u32 s20, 0
	s_cbranch_scc1 .Lgv_j0
	v_add_u32_e32 v4, 0x1000, v4
	global_store_dword v4, v3, s[26:27]
	s_branch .Lgv_fin
